# traffic reduction phase 3: layer-1 pool phase takes its row statistics from row sums accumulated by the layer-0 FFN-down epilogue (no statistics pass over x); on top of v50
# baseline (speedup 1.0000x reference)
.LBB0_353:
	s_andn2_b64 vcc, exec, s[2:3]
	s_lshl_b64 s[12:13], s[10:11], 23
	s_cbranch_vccnz .LBB0_358
	s_lshl_b64 s[8:9], s[10:11], 24
	v_writelane_b32 v253, s8, 20
	s_nop 1
	v_writelane_b32 v253, s9, 21
	v_readlane_b32 s23, v250, 44
	v_and_b32_e32 v2, 63, v0
	s_nop 1
	s_lshl_b32 s2, s23, 6
	v_add_u32_e32 v2, s2, v2
	v_cmp_gt_i32_e32 vcc, s20, v2
	s_and_saveexec_b64 s[18:19], vcc
	s_cbranch_execz .Lp1a_done
	s_lshl_b32 s3, s10, 12
	s_add_i32 s3, s3, s0
	v_add_u32_e32 v3, s3, v2
	v_lshlrev_b32_e32 v3, 3, v3
	v_readlane_b32 s4, v250, 38
	v_readlane_b32 s5, v250, 39
	s_nop 1
	s_add_u32 s4, s4, 0x130000
	s_addc_u32 s5, s5, 0
	s_nop 3
	global_load_dwordx2 v[4:5], v3, s[4:5]
	s_mov_b32 s2, 0x4f800000
	s_waitcnt vmcnt(0)
	v_cvt_f32_u32_e32 v5, v5
	v_cvt_f32_u32_e32 v4, v4
	v_fmac_f32_e32 v4, s2, v5
	v_mul_f32_e32 v4, 0x30000000, v4
	v_add_f32_e32 v4, 0x358637bd, v4
	v_rsq_f32_e32 v4, v4
	v_lshlrev_b32_e32 v5, 2, v2
	s_nop 0
	ds_write_b32 v5, v4
.Lp1a_done:
	s_or_b64 exec, exec, s[18:19]
.LBB0_358:
	s_bfe_u32 s2, s25, 0x60006
	s_lshl_b32 s4, s2, 6
	s_lshl_b32 s97, s2, 18
	v_writelane_b32 v253, s4, 49
	s_lshl_b32 s77, s2, 8
	s_mul_hi_i32 s5, s10, 0xc000
	s_mul_i32 s4, s10, 0xc000
	v_readlane_b32 s10, v255, 45
	s_add_u32 s4, s10, s4
	v_readlane_b32 s10, v255, 46
	s_addc_u32 s5, s10, s5
	v_writelane_b32 v252, s4, 25
	s_lshl_b64 s[12:13], s[12:13], 1
	v_readlane_b32 s10, v255, 43
	v_writelane_b32 v251, s26, 24
	v_writelane_b32 v252, s5, 26
	s_add_u32 s4, s10, s12
	v_readlane_b32 s11, v255, 44
	v_writelane_b32 v251, s25, 23
	s_addc_u32 s5, s11, s13
	v_writelane_b32 v251, s4, 49
	v_readlane_b32 s14, v255, 47
	s_mov_b32 s83, s95
	v_writelane_b32 v251, s5, 50
	s_add_u32 s4, s14, s12
	v_readlane_b32 s14, v255, 50
	s_addc_u32 s5, s14, s13
	s_lshl_b32 s82, s1, 12
	s_add_u32 s18, s82, 0xffff8000
	s_addc_u32 s19, 0, -1
	v_writelane_b32 v253, s18, 39
	v_writelane_b32 v252, s4, 28
	s_waitcnt lgkmcnt(0)
	v_writelane_b32 v253, s19, 40
	s_add_u32 s18, s82, 0xffff9000
	s_addc_u32 s19, 0, -1
	v_writelane_b32 v251, s18, 5
	v_writelane_b32 v252, s5, 29
	s_barrier
	v_writelane_b32 v251, s19, 6
	s_add_u32 s18, s82, 0xffffa000
	s_addc_u32 s19, 0, -1
	v_writelane_b32 v250, s18, 22
	s_nop 1
	v_writelane_b32 v250, s19, 23
	s_add_u32 s18, s82, 0xffffb000
	s_addc_u32 s19, 0, -1
	v_writelane_b32 v251, s18, 31
	s_nop 1
	v_writelane_b32 v251, s19, 32
	s_add_u32 s18, s82, 0xffffc000
	s_addc_u32 s19, 0, -1
	v_writelane_b32 v251, s18, 39
	s_nop 1
	v_writelane_b32 v251, s19, 40
	s_add_u32 s18, s82, 0xffffd000
	s_addc_u32 s19, 0, -1
	v_writelane_b32 v251, s18, 35
	s_nop 1
	v_writelane_b32 v251, s19, 36
	s_add_u32 s18, s82, 0xffffe000
	s_addc_u32 s19, 0, -1
	s_min_u32 s31, s1, 7
	s_add_i32 s31, s31, 1
	v_cvt_f32_ubyte0_e32 v2, s31
	v_div_scale_f32 v3, s[34:35], v2, v2, 1.0
	v_rcp_f32_e32 v4, v3
	v_writelane_b32 v252, s18, 5
	s_lshl_b32 s7, s7, 2
	s_or_b32 s15, s1, 1
	v_fma_f32 v5, -v3, v4, 1.0
	v_fmac_f32_e32 v4, v5, v4
	v_div_scale_f32 v5, vcc, 1.0, v2, 1.0
	v_writelane_b32 v252, s19, 6
	s_add_i32 s7, s7, 0
	v_mul_f32_e32 v6, v5, v4
	v_writelane_b32 v252, s7, 23
	v_fma_f32 v7, -v3, v6, v5
	s_min_u32 s7, s15, 7
	v_fmac_f32_e32 v6, v7, v4
	s_add_i32 s7, s7, 1
	v_fma_f32 v5, -v3, v6, v5
	v_cvt_f32_ubyte0_e32 v3, s7
	v_div_scale_f32 v7, s[34:35], v3, v3, 1.0
	v_rcp_f32_e32 v8, v7
	v_div_fmas_f32 v4, v5, v4, v6
	s_or_b32 s18, s1, 2
	s_lshl_b32 s7, s1, 11
	v_fma_f32 v5, -v7, v8, 1.0
	v_fmac_f32_e32 v8, v5, v8
	v_div_scale_f32 v6, vcc, 1.0, v3, 1.0
	v_writelane_b32 v252, s7, 27
	v_mul_f32_e32 v9, v6, v8
	s_min_u32 s7, s18, 7
	v_fma_f32 v5, -v7, v9, v6
	s_add_i32 s7, s7, 1
	v_fmac_f32_e32 v9, v5, v8
	v_cvt_f32_ubyte0_e32 v5, s7
	v_div_scale_f32 v10, s[34:35], v5, v5, 1.0
	v_rcp_f32_e32 v11, v10
	v_fma_f32 v6, -v7, v9, v6
	s_or_b32 s40, s1, 3
	v_div_fmas_f32 v8, v6, v8, v9
	v_fma_f32 v6, -v10, v11, 1.0
	v_fmac_f32_e32 v11, v6, v11
	v_div_scale_f32 v6, vcc, 1.0, v5, 1.0
	s_min_u32 s7, s40, 7
	v_mul_f32_e32 v7, v6, v11
	s_add_i32 s7, s7, 1
	v_fma_f32 v9, -v10, v7, v6
	v_cvt_f32_ubyte0_e32 v12, s7
	v_fmac_f32_e32 v7, v9, v11
	v_div_scale_f32 v9, s[34:35], v12, v12, 1.0
	v_rcp_f32_e32 v13, v9
	v_fma_f32 v6, -v10, v7, v6
	s_or_b32 s20, s1, 4
	v_div_fmas_f32 v10, v6, v11, v7
	v_fma_f32 v6, -v9, v13, 1.0
	v_fmac_f32_e32 v13, v6, v13
	v_div_scale_f32 v6, vcc, 1.0, v12, 1.0
	s_min_u32 s7, s20, 7
	v_mul_f32_e32 v7, v6, v13
	s_add_i32 s7, s7, 1
	v_fma_f32 v11, -v9, v7, v6
	v_cvt_f32_ubyte0_e32 v14, s7
	v_fmac_f32_e32 v7, v11, v13
	v_div_scale_f32 v11, s[34:35], v14, v14, 1.0
	v_rcp_f32_e32 v15, v11
	v_fma_f32 v6, -v9, v7, v6
	s_or_b32 s21, s1, 5
	v_div_fmas_f32 v13, v6, v13, v7
	v_fma_f32 v6, -v11, v15, 1.0
	v_fmac_f32_e32 v15, v6, v15
	v_div_scale_f32 v6, vcc, 1.0, v14, 1.0
	s_min_u32 s7, s21, 7
	v_mul_f32_e32 v7, v6, v15
	s_add_i32 s7, s7, 1
	v_fma_f32 v9, -v11, v7, v6
	v_cvt_f32_ubyte0_e32 v16, s7
	v_fmac_f32_e32 v7, v9, v15
	v_div_scale_f32 v9, s[34:35], v16, v16, 1.0
	v_rcp_f32_e32 v17, v9
	v_fma_f32 v6, -v11, v7, v6
	s_or_b32 s22, s1, 6
	v_div_fmas_f32 v15, v6, v15, v7
	v_fma_f32 v6, -v9, v17, 1.0
	v_fmac_f32_e32 v17, v6, v17
	v_div_scale_f32 v6, vcc, 1.0, v16, 1.0
	s_min_u32 s7, s22, 7
	v_mul_f32_e32 v7, v6, v17
	s_add_i32 s7, s7, 1
	v_fma_f32 v11, -v9, v7, v6
	v_cvt_f32_ubyte0_e32 v18, s7
	v_fmac_f32_e32 v7, v11, v17
	v_div_scale_f32 v11, s[34:35], v18, v18, 1.0
	v_rcp_f32_e32 v19, v11
	v_fma_f32 v6, -v9, v7, v6
	v_div_fmas_f32 v17, v6, v17, v7
	s_min_u32 s7, s1, 3
	v_fma_f32 v6, -v11, v19, 1.0
	v_fmac_f32_e32 v19, v6, v19
	v_div_scale_f32 v6, vcc, 1.0, v18, 1.0
	v_mul_f32_e32 v7, v6, v19
	v_fma_f32 v9, -v11, v7, v6
	v_fmac_f32_e32 v7, v9, v19
	s_add_i32 s7, s7, 1
	v_fma_f32 v6, -v11, v7, v6
	v_cvt_f32_ubyte0_e32 v20, s7
	s_min_u32 s7, s15, 3
	v_div_fmas_f32 v19, v6, v19, v7
	v_div_scale_f32 v6, s[64:65], v20, v20, 1.0
	s_add_i32 s7, s7, 1
	v_rcp_f32_e32 v7, v6
	v_cvt_f32_ubyte0_e32 v22, s7
	s_min_u32 s7, s18, 3
	s_add_i32 s7, s7, 1
	v_cvt_f32_ubyte0_e32 v24, s7
	s_ashr_i32 s7, s6, 31
	s_lshl_b64 s[6:7], s[6:7], 12
	v_fma_f32 v9, -v6, v7, 1.0
	v_writelane_b32 v251, s6, 33
	v_fmac_f32_e32 v7, v9, v7
	v_div_scale_f32 v9, vcc, 1.0, v20, 1.0
	v_div_scale_f32 v23, s[64:65], v22, v22, 1.0
	v_writelane_b32 v251, s7, 34
	s_lshl_b32 s6, s15, 11
	v_mul_f32_e32 v11, v9, v7
	v_rcp_f32_e32 v25, v23
	v_writelane_b32 v252, s6, 30
	s_lshl_b32 s6, s15, 12
	v_fma_f32 v21, -v6, v11, v9
	v_writelane_b32 v252, s6, 31
	v_fmac_f32_e32 v11, v21, v7
	v_fma_f32 v6, -v6, v11, v9
	v_writelane_b32 v252, s7, 32
	s_lshl_b32 s6, s18, 11
	v_writelane_b32 v252, s6, 33
	s_lshl_b32 s6, s18, 12
	v_div_fmas_f32 v21, v6, v7, v11
	v_fma_f32 v6, -v23, v25, 1.0
	v_writelane_b32 v252, s6, 34
	v_fmac_f32_e32 v25, v6, v25
	v_div_scale_f32 v6, vcc, 1.0, v22, 1.0
	v_writelane_b32 v252, s7, 35
	s_lshl_b32 s6, s40, 11
	v_mul_f32_e32 v7, v6, v25
	v_writelane_b32 v252, s6, 36
	s_lshl_b32 s6, s40, 12
	v_fma_f32 v9, -v23, v7, v6
	v_writelane_b32 v252, s6, 37
	v_fmac_f32_e32 v7, v9, v25
	v_div_scale_f32 v9, s[64:65], v24, v24, 1.0
	v_writelane_b32 v252, s7, 38
	s_lshl_b32 s6, s20, 11
	v_rcp_f32_e32 v11, v9
	v_writelane_b32 v252, s6, 39
	s_lshl_b32 s6, s20, 12
	v_writelane_b32 v252, s6, 40
	v_fma_f32 v6, -v23, v7, v6
	v_div_fmas_f32 v23, v6, v25, v7
	v_writelane_b32 v252, s7, 41
	s_lshl_b32 s6, s21, 11
	v_writelane_b32 v252, s6, 42
	s_lshl_b32 s6, s21, 12
	v_fma_f32 v6, -v9, v11, 1.0
	v_writelane_b32 v252, s6, 43
	v_fmac_f32_e32 v11, v6, v11
	v_div_scale_f32 v6, vcc, 1.0, v24, 1.0
	v_writelane_b32 v252, s7, 44
	s_lshl_b32 s6, s22, 11
	v_mul_f32_e32 v7, v6, v11
	v_writelane_b32 v252, s6, 45
	s_lshl_b32 s6, s22, 12
	s_or_b32 s5, s1, 7
	v_fma_f32 v25, -v9, v7, v6
	v_writelane_b32 v252, s6, 51
	s_or_b32 s24, s1, 8
	v_fmac_f32_e32 v7, v25, v11
	v_writelane_b32 v252, s7, 52
	s_lshl_b32 s7, s5, 11
	s_or_b32 s12, s1, 9
	v_fma_f32 v6, -v9, v7, v6
	v_writelane_b32 v252, s7, 47
	s_lshl_b32 s7, s24, 11
	v_div_fmas_f32 v25, v6, v11, v7
	s_lshl_b32 vcc_lo, s5, 12
	v_writelane_b32 v252, s7, 48
	s_lshl_b32 s5, s12, 11
	v_writelane_b32 v252, s5, 49
	s_lshl_b32 s6, s12, 12
	s_or_b32 s26, s1, 10
	v_writelane_b32 v252, s6, 54
	s_or_b32 s14, s1, 11
	s_lshl_b32 s5, s26, 11
	v_writelane_b32 v252, s7, 55
	s_or_b32 s28, s1, 12
	v_writelane_b32 v252, s5, 50
	s_lshl_b32 s5, s14, 11
	s_or_b32 s19, s1, 13
	v_writelane_b32 v252, s5, 53
	s_lshl_b32 s5, s28, 11
	s_or_b32 s30, s1, 14
	v_writelane_b32 v252, s5, 58
	s_lshl_b32 s5, s19, 11
	s_or_b32 s38, s1, 15
	v_writelane_b32 v252, s5, 61
	s_lshl_b32 s5, s30, 11
	s_or_b32 s4, s1, 16
	v_writelane_b32 v253, s5, 0
	s_lshl_b32 s5, s38, 11
	v_writelane_b32 v253, s5, 3
	s_lshl_b32 s5, s4, 11
	s_lshl_b32 s4, s4, 12
	s_or_b32 s10, s1, 17
	v_writelane_b32 v253, s5, 6
	v_writelane_b32 v252, s4, 3
	s_or_b32 s9, s1, 18
	s_or_b32 s11, s1, 19
	v_writelane_b32 v252, s5, 4
	s_lshl_b32 s5, s10, 11
	s_lshl_b32 s4, s10, 12
	v_writelane_b32 v253, s5, 9
	v_writelane_b32 v252, s4, 1
	s_or_b32 s8, s1, 20
	s_or_b32 s2, s1, 21
	v_writelane_b32 v252, s5, 2
	s_lshl_b32 s5, s9, 11
	s_lshl_b32 s4, s9, 12
	v_writelane_b32 v253, s5, 12
	v_writelane_b32 v252, s4, 7
	s_or_b32 s23, s1, 22
	s_or_b32 s27, s1, 23
	v_writelane_b32 v252, s5, 8
	s_lshl_b32 s5, s11, 11
	s_lshl_b32 s4, s11, 12
	v_writelane_b32 v251, s5, 37
	v_writelane_b32 v252, s4, 11
	s_or_b32 s29, s1, 24
	s_or_b32 s87, s1, 25
	v_writelane_b32 v252, s5, 12
	s_lshl_b32 s5, s8, 11
	s_lshl_b32 s4, s8, 12
	v_writelane_b32 v253, s5, 15
	v_writelane_b32 v252, s4, 15
	s_or_b32 s93, s1, 27
	s_or_b32 s47, s1, 28
	v_writelane_b32 v252, s5, 16
	s_lshl_b32 s5, s2, 11
	v_writelane_b32 v253, s5, 16
	s_lshl_b32 s5, s23, 11
	v_writelane_b32 v254, s5, 1
	s_lshl_b32 s5, s27, 11
	v_writelane_b32 v254, s5, 5
	s_lshl_b32 s5, s29, 11
	v_writelane_b32 v254, s5, 3
	s_lshl_b32 s5, s87, 11
	s_or_b32 s3, s1, 44
	s_lshl_b32 s2, s2, 12
	v_writelane_b32 v253, s5, 25
	s_lshl_b32 s5, s93, 11
	s_or_b32 s45, s1, 26
	s_or_b32 s35, s1, 29
	v_writelane_b32 v252, s2, 19
	v_writelane_b32 v253, s5, 19
	s_lshl_b32 s5, s47, 11
	s_or_b32 s41, s1, 30
	s_or_b32 s39, s1, 31
	v_writelane_b32 v252, s3, 20
	s_lshl_b32 s2, s45, 11
	v_writelane_b32 v253, s5, 28
	s_lshl_b32 s5, s35, 11
	s_or_b32 s51, s1, 32
	s_or_b32 s91, s1, 33
	v_writelane_b32 v254, s2, 49
	v_writelane_b32 v253, s5, 24
	s_lshl_b32 s5, s41, 11
	s_lshl_b32 s2, s39, 11
	s_or_b32 s37, s1, 34
	s_or_b32 s57, s1, 36
	v_writelane_b32 v253, s5, 29
	v_writelane_b32 v254, s2, 27
	s_lshl_b32 s2, s51, 11
	s_lshl_b32 s9, s91, 11
	s_or_b32 s61, s1, 37
	s_or_b32 s49, s1, 38
	v_writelane_b32 v254, s2, 25
	v_writelane_b32 v253, s9, 33
	s_lshl_b32 s2, s37, 11
	s_lshl_b32 s4, s57, 11
	s_or_b32 s13, s1, 42
	v_writelane_b32 v251, s2, 53
	s_lshl_b32 s2, s37, 12
	v_writelane_b32 v253, s4, 17
	s_lshl_b32 s4, s61, 11
	s_lshl_b32 s9, s49, 11
	s_or_b32 s58, s1, 35
	s_or_b32 s17, s1, 39
	s_or_b32 s43, s1, 43
	v_writelane_b32 v251, s2, 55
	v_writelane_b32 v254, s4, 11
	v_writelane_b32 v253, s9, 30
	s_lshl_b32 s4, s13, 11
	s_or_b32 s59, s1, 41
	s_or_b32 s36, s1, 45
	v_writelane_b32 v251, s3, 56
	s_lshl_b32 s2, s58, 11
	s_lshl_b32 s9, s17, 11
	v_writelane_b32 v253, s4, 41
	s_lshl_b32 s68, s13, 12
	s_lshl_b32 s13, s43, 11
	s_or_b32 s44, s1, 46
	s_lshl_b32 s62, s14, 12
	v_writelane_b32 v251, s2, 51
	v_writelane_b32 v254, s9, 9
	s_lshl_b32 s2, s59, 11
	v_writelane_b32 v253, s13, 36
	s_lshl_b32 s13, s3, 11
	s_lshl_b32 s14, s3, 12
	s_lshl_b32 s3, s36, 11
	v_writelane_b32 v251, s2, 0
	v_writelane_b32 v253, s13, 37
	v_writelane_b32 v254, s3, 21
	s_lshl_b32 s3, s44, 11
	s_lshl_b32 s2, s44, 12
	s_or_b32 s25, s1, 47
	v_writelane_b32 v253, s3, 38
	v_writelane_b32 v255, s2, 51
	s_or_b32 s69, s1, 48
	s_or_b32 s55, s1, 49
	v_writelane_b32 v255, s3, 52
	s_lshl_b32 s3, s25, 11
	v_writelane_b32 v254, s3, 19
	s_lshl_b32 s2, s69, 11
	s_or_b32 s46, s1, 50
	v_writelane_b32 v254, s2, 23
	s_lshl_b32 s2, s55, 11
	s_or_b32 s89, s1, 51
	v_writelane_b32 v254, s2, 33
	s_lshl_b32 s2, s46, 11
	v_writelane_b32 v254, s2, 29
	s_lshl_b32 s2, s89, 11
	v_writelane_b32 v253, s2, 42
	s_lshl_b32 s2, s89, 12
	s_or_b32 s71, s1, 52
	v_writelane_b32 v253, s2, 53
	s_or_b32 s75, s1, 55
	s_or_b32 s73, s1, 54
	v_writelane_b32 v253, s3, 54
	s_lshl_b32 s2, s71, 11
	v_writelane_b32 v254, s2, 37
	s_lshl_b32 s2, s75, 11
	v_writelane_b32 v253, s2, 18
	s_lshl_b32 s2, s75, 12
	s_or_b32 s65, s1, 60
	v_writelane_b32 v255, s2, 53
	s_lshl_b32 s5, s73, 11
	s_lshl_b32 s4, s65, 12
	v_writelane_b32 v255, s3, 54
	s_or_b32 s16, s1, 40
	s_or_b32 s67, s1, 62
	v_writelane_b32 v255, s4, 55
	s_or_b32 s81, s1, 61
	s_lshl_b32 s42, s19, 12
	s_lshl_b32 s19, s16, 11
	s_lshl_b32 s54, s16, 12
	s_lshl_b32 s3, s65, 11
	v_writelane_b32 v255, s5, 56
	s_lshl_b32 s16, s67, 12
	s_add_i32 s94, s1, -1
	s_or_b32 s79, s1, 53
	s_or_b32 s31, s1, 56
	s_or_b32 s56, s1, 57
	s_or_b32 s53, s1, 58
	s_or_b32 s63, s1, 59
	s_or_b32 s1, s1, 63
	s_lshl_b32 s22, s17, 12
	v_writelane_b32 v253, s3, 63
	s_lshl_b32 s3, s81, 11
	v_writelane_b32 v255, s16, 57
	v_writelane_b32 v253, s3, 61
	s_lshl_b32 s3, s1, 11
	v_writelane_b32 v255, s17, 58
	v_writelane_b32 v255, s3, 59
	s_lshl_b32 s16, s1, 12
	v_writelane_b32 v255, s16, 60
	s_lshl_b32 s2, s31, 11
	s_lshl_b32 s70, s24, 12
	v_writelane_b32 v255, s17, 61
	s_lshl_b64 s[16:17], s[94:95], 12
	s_lshl_b32 s64, s26, 12
	s_lshl_b32 s48, s28, 12
	s_lshl_b32 s76, s30, 12
	s_lshl_b32 s28, s38, 12
	s_lshl_b32 s96, s23, 12
	s_lshl_b32 s66, s27, 12
	s_lshl_b32 s78, s29, 12
	s_lshl_b32 s86, s87, 12
	s_lshl_b32 s80, s45, 12
	s_lshl_b32 s40, s93, 12
	s_lshl_b32 s34, s47, 12
	s_lshl_b32 s26, s35, 12
	s_lshl_b32 s74, s41, 12
	s_lshl_b32 s60, s39, 12
	s_lshl_b32 s30, s51, 12
	s_lshl_b32 s72, s91, 12
	s_lshl_b32 s92, s58, 12
	s_lshl_b32 s24, s57, 12
	s_lshl_b32 s20, s61, 12
	s_lshl_b32 s58, s49, 12
	s_lshl_b32 s88, s59, 12
	s_lshl_b32 s18, s43, 12
	s_lshl_b32 s12, s36, 12
	s_lshl_b32 s36, s25, 12
	s_lshl_b32 s44, s69, 12
	s_lshl_b32 s10, s55, 12
	s_lshl_b32 s46, s46, 12
	s_lshl_b32 s52, s71, 12
	s_lshl_b32 s39, s79, 11
	s_lshl_b32 s38, s79, 12
	s_lshl_b32 s90, s73, 12
	v_writelane_b32 v254, s2, 41
	s_lshl_b32 s50, s31, 12
	s_lshl_b32 s7, s56, 11
	s_lshl_b32 s56, s56, 12
	s_lshl_b32 s2, s53, 11
	s_lshl_b32 s8, s53, 12
	s_lshl_b32 s9, s63, 11
	s_lshl_b32 s6, s63, 12
	s_lshl_b32 s4, s81, 12
	s_lshl_b32 s13, s67, 11
	v_writelane_b32 v253, s16, 47
	s_mov_b32 s65, s95
	v_writelane_b32 v254, s64, 7
	v_writelane_b32 v253, s17, 48
	s_add_u32 s16, s82, 0xffff1000
	s_addc_u32 s17, 0, -1
	v_writelane_b32 v251, s16, 13
	v_writelane_b32 v254, s65, 8
	s_mov_b32 s49, s95
	v_writelane_b32 v251, s17, 14
	s_add_u32 s16, s82, 0xffff2000
	s_addc_u32 s17, 0, -1
	v_writelane_b32 v251, s16, 15
	v_writelane_b32 v254, s48, 13
	s_mov_b32 s43, s95
	v_writelane_b32 v251, s17, 16
	s_add_u32 s16, s82, 0xffff3000
	s_addc_u32 s17, 0, -1
	v_writelane_b32 v251, s16, 17
	v_writelane_b32 v254, s49, 14
	s_mov_b32 vcc_hi, s95
	v_writelane_b32 v251, s17, 18
	s_add_u32 s16, s82, 0xffff4000
	s_addc_u32 s17, 0, -1
	v_writelane_b32 v251, s16, 19
	v_writelane_b32 v254, s42, 15
	s_mov_b32 s27, s95
	v_writelane_b32 v251, s17, 20
	s_add_u32 s16, s82, 0xffff5000
	s_addc_u32 s17, 0, -1
	v_writelane_b32 v251, s16, 25
	v_writelane_b32 v254, s43, 16
	s_mov_b32 s71, s95
	v_writelane_b32 v251, s17, 26
	s_add_u32 s16, s82, 0xffff6000
	s_addc_u32 s17, 0, -1
	v_writelane_b32 v251, s16, 27
	s_mov_b32 s61, s95
	s_mov_b32 s63, s95
	v_writelane_b32 v251, s17, 28
	s_add_u32 s16, s82, 0xffff7000
	s_addc_u32 s17, 0, -1
	v_writelane_b32 v251, s16, 29
	s_mov_b32 s31, s95
	s_mov_b32 s67, s95
	v_writelane_b32 v251, s17, 30
	v_readlane_b32 s16, v253, 20
	v_readlane_b32 s17, v253, 21
	s_add_u32 s1, s16, s97
	s_addc_u32 s3, s17, 0
	v_readlane_b32 s16, v255, 48
	v_readlane_b32 s17, v255, 49
	s_add_u32 s16, s16, s1
	s_addc_u32 s17, s17, s3
	v_writelane_b32 v253, s16, 51
	s_lshl_b32 s0, s0, 2
	s_sub_i32 s0, s77, s0
	v_writelane_b32 v253, s17, 52
	v_readlane_b32 s16, v252, 31
	v_readlane_b32 s17, v252, 32
	s_mov_b32 s17, s95
	v_writelane_b32 v252, s16, 31
	v_writelane_b32 v253, s82, 20
	s_mov_b32 s77, s95
	v_writelane_b32 v252, s17, 32
	v_writelane_b32 v253, s83, 21
	v_readlane_b32 s16, v252, 34
	v_readlane_b32 s17, v252, 35
	s_mov_b32 s17, s95
	v_writelane_b32 v252, s16, 34
	v_writelane_b32 v253, vcc_lo, 26
	v_writelane_b32 v254, s76, 17
	v_writelane_b32 v252, s17, 35
	v_writelane_b32 v253, vcc_hi, 27
	v_readlane_b32 s16, v252, 37
	v_readlane_b32 s17, v252, 38
	s_mov_b32 s17, s95
	v_writelane_b32 v252, s16, 37
	v_writelane_b32 v251, s26, 63
	v_writelane_b32 v253, s70, 31
	v_writelane_b32 v252, s17, 38
	v_writelane_b32 v254, s77, 18
	v_readlane_b32 s16, v252, 40
	v_readlane_b32 s17, v252, 41
	s_mov_b32 s17, s95
	v_writelane_b32 v252, s16, 40
	s_mov_b32 s97, s95
	v_writelane_b32 v251, s60, 41
	v_writelane_b32 v252, s17, 41
	v_writelane_b32 v253, s71, 32
	v_readlane_b32 s16, v252, 43
	v_readlane_b32 s17, v252, 44
	s_mov_b32 s17, s95
	v_writelane_b32 v252, s16, 43
	v_writelane_b32 v254, s96, 31
	v_writelane_b32 v251, s61, 42
	v_writelane_b32 v252, s17, 44
	v_writelane_b32 v253, s62, 22
	v_readlane_b32 s16, v252, 51
	v_readlane_b32 s17, v252, 52
	s_mov_b32 s17, s95
	v_writelane_b32 v252, s16, 51
	v_writelane_b32 v254, s97, 32
	v_writelane_b32 v251, s30, 59
	v_writelane_b32 v252, s17, 52
	v_writelane_b32 v253, s63, 23
	v_readlane_b32 s16, v252, 54
	v_readlane_b32 s17, v252, 55
	s_mov_b32 s17, s95
	v_writelane_b32 v252, s16, 54
	s_mov_b32 s29, s95
	v_writelane_b32 v254, s66, 35
	v_writelane_b32 v252, s17, 55
	v_writelane_b32 v251, s31, 60
	v_readlane_b32 s16, v252, 3
	v_readlane_b32 s17, v252, 4
	s_mov_b32 s17, s95
	v_writelane_b32 v252, s16, 3
	v_writelane_b32 v253, s28, 34
	v_writelane_b32 v254, s67, 36
	v_writelane_b32 v252, s17, 4
	s_mov_b32 s87, s95
	v_readlane_b32 s16, v252, 1
	v_readlane_b32 s17, v252, 2
	s_mov_b32 s17, s95
	v_writelane_b32 v252, s16, 1
	v_readlane_b32 s62, v251, 55
	s_mov_b32 s73, s95
	v_writelane_b32 v252, s17, 2
	v_writelane_b32 v253, s29, 35
	v_readlane_b32 s16, v252, 7
	v_readlane_b32 s17, v252, 8
	s_mov_b32 s17, s95
	v_writelane_b32 v252, s16, 7
	s_mov_b32 s79, s95
	v_writelane_b32 v254, s86, 45
	v_writelane_b32 v252, s17, 8
	v_readlane_b32 s63, v251, 56
	v_readlane_b32 s16, v252, 11
	v_readlane_b32 s17, v252, 12
	s_mov_b32 s17, s95
	v_writelane_b32 v252, s16, 11
	v_writelane_b32 v251, s72, 61
	v_writelane_b32 v253, s78, 43
	v_writelane_b32 v252, s17, 12
	v_writelane_b32 v254, s87, 46
	v_readlane_b32 s16, v252, 15
	v_readlane_b32 s17, v252, 16
	s_mov_b32 s17, s95
	v_writelane_b32 v252, s16, 15
	s_mov_b32 s81, s95
	v_writelane_b32 v251, s73, 62
	v_writelane_b32 v252, s17, 16
	s_mov_b32 s93, s95
	v_readlane_b32 s16, v252, 19
	v_writelane_b32 v253, s79, 44
	v_writelane_b32 v254, s80, 39
	s_mov_b32 s75, s95
	v_writelane_b32 v251, s92, 55
	v_readlane_b32 s17, v252, 20
	v_writelane_b32 v254, s81, 40
	s_mov_b32 s41, s95
	v_writelane_b32 v253, s74, 45
	v_writelane_b32 v251, s93, 56
	s_mov_b32 s25, s95
	s_mov_b32 s17, s95
	v_writelane_b32 v254, s40, 43
	v_writelane_b32 v253, s75, 46
	v_writelane_b32 v251, s24, 57
	s_mov_b32 s11, s95
	v_readlane_b32 s1, v250, 63
	v_readlane_b32 s42, v255, 51
	v_writelane_b32 v252, s16, 19
	v_writelane_b32 v254, s41, 44
	s_mov_b32 s35, s95
	v_readlane_b32 s60, v255, 60
	v_writelane_b32 v251, s25, 58
	s_mov_b64 s[40:41], s[10:11]
	v_readlane_b32 s10, v253, 53
	v_readlane_b32 s78, v255, 53
	v_readlane_b32 s74, v255, 55
	v_readlane_b32 s24, v255, 57
	v_add_u32_e32 v160, s1, v0
	v_div_fixup_f32 v6, v4, v2, 1.0
	v_div_fixup_f32 v8, v8, v3, 1.0
	v_div_fixup_f32 v10, v10, v5, 1.0
	v_div_fixup_f32 v12, v13, v12, 1.0
	v_div_fixup_f32 v14, v15, v14, 1.0
	v_div_fixup_f32 v16, v17, v16, 1.0
	v_div_fixup_f32 v18, v19, v18, 1.0
	v_readlane_b32 s43, v255, 52
	v_writelane_b32 v252, s17, 20
	v_writelane_b32 v254, s34, 47
	v_readlane_b32 s61, v255, 61
	s_mov_b32 s73, s19
	s_mov_b32 s19, s95
	v_readlane_b32 s11, v253, 54
	v_readlane_b32 s79, v255, 54
	s_mov_b32 s67, s9
	v_readlane_b32 s75, v255, 56
	s_mov_b32 s9, s95
	v_readlane_b32 s25, v255, 58
	v_div_fixup_f32 v20, v21, v20, 1.0
	v_div_fixup_f32 v22, v23, v22, 1.0
	v_div_fixup_f32 v24, v25, v24, 1.0
	s_add_i32 s0, s0, 0
	v_readlane_b32 s1, v255, 59
	v_lshlrev_b32_e32 v161, 1, v160
	v_mov_b32_e32 v7, v6
	v_mov_b32_e32 v9, v8
	v_mov_b32_e32 v11, v10
	v_mov_b32_e32 v13, v12
	v_mov_b32_e32 v15, v14
	v_mov_b32_e32 v17, v16
	v_mov_b32_e32 v19, v18
	v_writelane_b32 v254, s35, 48
	v_writelane_b32 v252, s27, 0
	s_mov_b32 s66, s13
	s_mov_b32 s63, s95
	s_mov_b32 s21, s95
	s_mov_b32 s59, s95
	s_mov_b32 s23, s95
	s_mov_b32 s55, s95
	s_mov_b32 s89, s95
	s_mov_b32 s69, s95
	s_mov_b64 s[92:93], s[18:19]
	s_mov_b32 s15, s95
	s_mov_b32 s13, s95
	s_mov_b32 s43, s95
	s_mov_b32 s37, s95
	s_mov_b32 s45, s95
	s_mov_b32 s47, s95
	s_mov_b32 s48, s5
	s_mov_b32 s65, s39
	s_mov_b32 s11, s95
	s_mov_b32 s53, s95
	s_mov_b32 s39, s95
	s_mov_b32 s91, s95
	s_mov_b32 s86, s2
	s_mov_b32 s49, s7
	s_mov_b32 s79, s95
	s_mov_b32 s51, s95
	s_mov_b32 s57, s95
	s_mov_b64 s[34:35], s[8:9]
	s_mov_b32 s7, s95
	s_mov_b32 s75, s95
	s_mov_b32 s5, s95
	s_mov_b32 s25, s95
	s_mov_b32 s61, s95
	v_mov_b32_e32 v21, v20
	v_mov_b32_e32 v23, v22
	v_mov_b32_e32 v25, v24
	v_writelane_b32 v253, s0, 53
	s_mov_b32 s0, 0
	s_lshl_b32 s80, s1, 1
	v_readlane_b32 s64, v251, 0
	s_mov_b64 s[2:3], -1
	s_branch .LBB0_360

.LBB0_1213:
	s_add_i32 s0, s68, -3
	s_cmp_gt_u32 s0, -3
	s_cselect_b64 s[10:11], -1, 0
	s_add_u32 s12, s6, 0x30900000
	s_addc_u32 s13, s7, 0
	s_lshl_b64 s[0:1], s[94:95], 2
	s_add_u32 s0, s6, s0
	s_addc_u32 s1, s7, s1
	s_add_u32 s14, s0, 0x468000
	s_addc_u32 s15, s1, 0
	s_add_u32 s16, s0, 0x408000
	s_addc_u32 s17, s1, 0
	s_add_u32 s18, s6, 0x13700000
	s_addc_u32 s19, s7, 0
	s_add_u32 s20, s6, 0x440000
	s_addc_u32 s21, s7, 0
	s_add_u32 s22, s6, 0x17700000
	v_readlane_b32 s0, v251, 21
	s_addc_u32 s23, s7, 0
	v_readlane_b32 s1, v251, 22
	s_and_b64 s[0:1], s[0:1], exec
	s_mov_b32 s0, 0x80000
	s_cselect_b32 s0, s0, 0xa0000
	s_add_u32 s0, s6, s0
	v_and_b32_e32 v3, 15, v2
	s_addc_u32 s1, s7, 0
	v_or_b32_e32 v4, s72, v3
	s_add_u32 s24, s0, 0x10000
	v_and_b32_e32 v5, 48, v2
	v_lshlrev_b32_e32 v6, 6, v4
	s_movk_i32 s0, 0x3c0
	v_lshlrev_b32_e32 v4, 2, v4
	v_and_or_b32 v6, v6, s0, v5
	v_and_b32_e32 v4, 32, v4
	v_readlane_b32 s0, v254, 51
	v_lshlrev_b32_e32 v2, 2, v2
	s_addc_u32 s25, s1, 0
	s_cmp_lg_u32 s68, 0
	s_cbranch_scc1 .Lrs9_skip
	s_add_u32 s24, s6, 0x130000
	s_addc_u32 s25, s7, 0
.Lrs9_skip:
	v_bitop3_b32 v4, v6, s0, v4 bitop3:0xde
	v_lshl_or_b32 v3, v3, 6, v5
	v_and_b32_e32 v2, 32, v2
	v_readlane_b32 s0, v255, 0
	s_add_i32 s50, s42, 0x18000
	s_waitcnt vmcnt(2)
	s_barrier
	v_bitop3_b32 v2, v3, s0, v2 bitop3:0xde
	s_add_u32 s0, s30, 0x80
	s_addc_u32 s1, s31, 0
	s_mov_b32 m0, s50
	s_nop 0
	global_load_lds_dwordx4 v224, s[0:1]
	s_add_i32 s51, s42, 0x1a000
	s_add_i32 s52, s42, 0x8000
	s_mov_b32 m0, s51
	s_nop 0
	global_load_lds_dwordx4 v226, s[0:1]
	s_add_u32 s0, s8, 0x80
	s_addc_u32 s1, s9, 0
	s_mov_b32 m0, s52
	s_nop 0
	global_load_lds_dwordx4 v0, s[0:1]
	s_add_i32 s53, s42, 0xa000
	s_add_i32 s54, s42, 0x1c000
	s_mov_b32 m0, s53
	s_nop 0
	global_load_lds_dwordx4 v225, s[0:1]
	s_add_u32 s0, s30, 0x160080
	s_addc_u32 s1, s31, 0
	s_mov_b32 m0, s54
	s_nop 0
	global_load_lds_dwordx4 v224, s[0:1]
	s_add_i32 s55, s42, 0x1e000
	s_mov_b32 m0, s55
	s_nop 0
	global_load_lds_dwordx4 v226, s[0:1]
	s_waitcnt vmcnt(6)
	v_readlane_b32 s4, v255, 32
	s_mov_b32 s34, 0
	s_add_i32 s56, s42, 0xc000
	s_add_i32 s57, s42, 0xe000
	v_add_u32_e32 v227, 0, v2
	v_add_u32_e32 v228, 0, v4
	v_readlane_b32 s0, v255, 11
	s_mov_b32 s1, s4
	s_barrier
	v_readlane_b32 s5, v255, 33
	s_branch .LBB0_1216

.LBB0_1306:
	s_cmp_eq_u32 s68, 0
	s_cselect_b64 s[88:89], -1, 0
	s_or_b64 s[88:89], s[88:89], s[10:11]
	s_and_b64 vcc, exec, s[88:89]
	s_cbranch_vccz .LBB0_1326
